# speedup vs baseline: 1.0058x; 1.0058x over previous
; DEV unsigned cvtpk(float lo, float hi) { f32x2_t v = {lo, hi}; bf16x2_t b = __builtin_convertvector(v, bf16x2_t); return __builtin_bit_cast(unsigned, b); }
; template <int MODE>
; DEV void gemm_phase(const bf16_t* __restrict__ A, const bf16_t* __restrict__ Bt, int M, int N, int K, bf16_t* __restrict__ Out, int ldo,
;                     const float* __restrict__ rstd, const float* __restrict__ rope) {
;     ...
;     if constexpr (MODE == G_GATEUP) {
; #pragma unroll
;       for (int ai = 0; ai < 2; ++ai)
; #pragma unroll
;         for (int m = 0; m < 4; ++m) {
;           const int row = brow + ai * HALF + wr * 64 + m * 16 + fr; const float rs = rstd[row];
;           float a8[8];
; #pragma unroll
;           for (int n = 0; n < 2; ++n)
; #pragma unroll
;             for (int j = 0; j < 4; ++j) { const float gv = acc[ai][0][m][n][j] * rs, uv = acc[ai][1][m][n][j] * rs;
;               a8[n * 4 + j] = gv * __builtin_amdgcn_rcpf(1.f + __builtin_amdgcn_exp2f(-gv * LOG2E)) * uv; }
;           u32x4 w = {cvtpk(a8[0], a8[1]), cvtpk(a8[2], a8[3]), cvtpk(a8[4], a8[5]), cvtpk(a8[6], a8[7])};
;           *reinterpret_cast<u32x4*>(Out + (size_t)row * ldo + pn * 128 + wc * 32 + fq * 8) = w; }
.LBB0_621:
	v_lshl_add_u32 v142, s35, 8, v144
	v_ashrrev_i32_e32 v143, 31, v142
	v_lshl_add_u64 v[148:149], v[142:143], 2, s[68:69]
	global_load_dword v152, v[148:149], off
	global_load_dword v154, v[148:149], off offset:64
	global_load_dword v156, v[148:149], off offset:128
	global_load_dword v158, v[148:149], off offset:192
	global_load_dword v160, v[148:149], off offset:512
	global_load_dword v162, v[148:149], off offset:576
	global_load_dword v164, v[148:149], off offset:640
	global_load_dword v166, v[148:149], off offset:704
	s_lshl_b32 s18, s34, 7
	s_ashr_i32 s19, s18, 31
	v_lshl_add_u64 v[140:141], s[18:19], 1, v[134:135]
	s_movk_i32 s9, 0x2c00
	s_andn2_b64 vcc, exec, s[12:13]
	s_waitcnt vmcnt(0)
	v_pk_mul_f32 v[124:125], v[124:125], v[152:153] op_sel_hi:[1,0]
	s_nop 0
	v_mul_f32_e32 v143, 0xbfb8aa3b, v124
	v_exp_f32_e32 v143, v143
	v_pk_mul_f32 v[116:117], v[116:117], v[152:153] op_sel_hi:[1,0]
	v_pk_mul_f32 v[118:119], v[118:119], v[152:153] op_sel_hi:[1,0]
	v_pk_mul_f32 v[120:121], v[120:121], v[152:153] op_sel_hi:[1,0]
	v_add_f32_e32 v143, 1.0, v143
	v_rcp_f32_e32 v150, v143
	v_mul_f32_e32 v143, 0xbfb8aa3b, v125
	v_exp_f32_e32 v143, v143
	v_pk_mul_f32 v[112:113], v[112:113], v[152:153] op_sel_hi:[1,0]
	v_pk_mul_f32 v[114:115], v[114:115], v[152:153] op_sel_hi:[1,0]
	v_add_f32_e32 v143, 1.0, v143
	v_rcp_f32_e32 v151, v143
	s_nop 0
	v_pk_mul_f32 v[124:125], v[124:125], v[150:151]
	s_nop 0
	v_pk_mul_f32 v[116:117], v[116:117], v[124:125]
	v_pk_mul_f32 v[124:125], v[126:127], v[152:153] op_sel_hi:[1,0]
	s_nop 0
	v_mul_f32_e32 v126, 0xbfb8aa3b, v124
	v_mul_f32_e32 v127, 0xbfb8aa3b, v125
	v_exp_f32_e32 v126, v126
	v_exp_f32_e32 v127, v127
	v_add_f32_e32 v126, 1.0, v126
	v_add_f32_e32 v127, 1.0, v127
	v_rcp_f32_e32 v126, v126
	v_rcp_f32_e32 v127, v127
	s_nop 0
	v_pk_mul_f32 v[124:125], v[124:125], v[126:127]
	s_nop 0
	v_pk_mul_f32 v[118:119], v[118:119], v[124:125]
	v_mul_f32_e32 v124, 0xbfb8aa3b, v120
	v_mul_f32_e32 v125, 0xbfb8aa3b, v121
	v_exp_f32_e32 v124, v124
	v_exp_f32_e32 v125, v125
	v_add_f32_e32 v124, 1.0, v124
	v_add_f32_e32 v125, 1.0, v125
	v_rcp_f32_e32 v124, v124
	v_rcp_f32_e32 v125, v125
	s_nop 0
	v_pk_mul_f32 v[120:121], v[120:121], v[124:125]
	s_nop 0
	v_pk_mul_f32 v[120:121], v[112:113], v[120:121]
	v_pk_mul_f32 v[112:113], v[122:123], v[152:153] op_sel_hi:[1,0]
	s_nop 0
	v_mul_f32_e32 v122, 0xbfb8aa3b, v112
	v_mul_f32_e32 v123, 0xbfb8aa3b, v113
	v_exp_f32_e32 v122, v122
	v_exp_f32_e32 v123, v123
	v_add_f32_e32 v122, 1.0, v122
	v_add_f32_e32 v123, 1.0, v123
	v_rcp_f32_e32 v122, v122
	v_rcp_f32_e32 v123, v123
	s_nop 0
	v_pk_mul_f32 v[112:113], v[112:113], v[122:123]
	s_nop 0
	v_pk_mul_f32 v[122:123], v[114:115], v[112:113]
	v_cvt_pk_bf16_f32 v112, v116, v117
	v_cvt_pk_bf16_f32 v113, v118, v119
	v_cvt_pk_bf16_f32 v114, v120, v121
	v_cvt_pk_bf16_f32 v115, v122, v123
	v_mad_i64_i32 v[116:117], s[18:19], v142, s9, v[140:141]
	global_store_dwordx4 v[116:117], v[112:115], off
	s_nop 1
	v_or_b32_e32 v112, 16, v142
	v_pk_mul_f32 v[108:109], v[108:109], v[154:155] op_sel_hi:[1,0]
	s_nop 0
	v_mul_f32_e32 v113, 0xbfb8aa3b, v108
	v_exp_f32_e32 v113, v113
	v_pk_mul_f32 v[100:101], v[100:101], v[154:155] op_sel_hi:[1,0]
	v_pk_mul_f32 v[102:103], v[102:103], v[154:155] op_sel_hi:[1,0]
	v_pk_mul_f32 v[104:105], v[104:105], v[154:155] op_sel_hi:[1,0]
	v_add_f32_e32 v113, 1.0, v113
	v_rcp_f32_e32 v116, v113
	v_mul_f32_e32 v113, 0xbfb8aa3b, v109
	v_exp_f32_e32 v113, v113
	v_pk_mul_f32 v[96:97], v[96:97], v[154:155] op_sel_hi:[1,0]
	v_pk_mul_f32 v[98:99], v[98:99], v[154:155] op_sel_hi:[1,0]
	v_add_f32_e32 v113, 1.0, v113
	v_rcp_f32_e32 v117, v113
	s_nop 0
	v_pk_mul_f32 v[108:109], v[108:109], v[116:117]
	s_nop 0
	v_pk_mul_f32 v[100:101], v[100:101], v[108:109]
	v_pk_mul_f32 v[108:109], v[110:111], v[154:155] op_sel_hi:[1,0]
	s_nop 0
	v_mul_f32_e32 v110, 0xbfb8aa3b, v108
	v_mul_f32_e32 v111, 0xbfb8aa3b, v109
	v_exp_f32_e32 v110, v110
	v_exp_f32_e32 v111, v111
	v_add_f32_e32 v110, 1.0, v110
	v_add_f32_e32 v111, 1.0, v111
	v_rcp_f32_e32 v110, v110
	v_rcp_f32_e32 v111, v111
	s_nop 0
	v_pk_mul_f32 v[108:109], v[108:109], v[110:111]
	s_nop 0
	v_pk_mul_f32 v[102:103], v[102:103], v[108:109]
	v_mul_f32_e32 v108, 0xbfb8aa3b, v104
	v_mul_f32_e32 v109, 0xbfb8aa3b, v105
	v_exp_f32_e32 v108, v108
	v_exp_f32_e32 v109, v109
	v_add_f32_e32 v108, 1.0, v108
	v_add_f32_e32 v109, 1.0, v109
	v_rcp_f32_e32 v108, v108
	v_rcp_f32_e32 v109, v109
	s_nop 0
	v_pk_mul_f32 v[104:105], v[104:105], v[108:109]
	s_nop 0
	v_pk_mul_f32 v[104:105], v[96:97], v[104:105]
	v_pk_mul_f32 v[96:97], v[106:107], v[154:155] op_sel_hi:[1,0]
	s_nop 0
	v_mul_f32_e32 v106, 0xbfb8aa3b, v96
	v_mul_f32_e32 v107, 0xbfb8aa3b, v97
	v_exp_f32_e32 v106, v106
	v_exp_f32_e32 v107, v107
	v_add_f32_e32 v106, 1.0, v106
	v_add_f32_e32 v107, 1.0, v107
	v_rcp_f32_e32 v106, v106
	v_rcp_f32_e32 v107, v107
	s_nop 0
	v_pk_mul_f32 v[96:97], v[96:97], v[106:107]
	s_nop 0
	v_pk_mul_f32 v[106:107], v[98:99], v[96:97]
	v_cvt_pk_bf16_f32 v96, v100, v101
	v_cvt_pk_bf16_f32 v97, v102, v103
	v_cvt_pk_bf16_f32 v98, v104, v105
	v_cvt_pk_bf16_f32 v99, v106, v107
	v_mad_i64_i32 v[100:101], s[18:19], v112, s9, v[140:141]
	global_store_dwordx4 v[100:101], v[96:99], off
	s_nop 1
	v_or_b32_e32 v96, 32, v142
	v_pk_mul_f32 v[92:93], v[92:93], v[156:157] op_sel_hi:[1,0]
	s_nop 0
	v_mul_f32_e32 v97, 0xbfb8aa3b, v92
	v_exp_f32_e32 v97, v97
	v_pk_mul_f32 v[84:85], v[84:85], v[156:157] op_sel_hi:[1,0]
	v_pk_mul_f32 v[86:87], v[86:87], v[156:157] op_sel_hi:[1,0]
	v_pk_mul_f32 v[88:89], v[88:89], v[156:157] op_sel_hi:[1,0]
	v_add_f32_e32 v97, 1.0, v97
	v_rcp_f32_e32 v100, v97
	v_mul_f32_e32 v97, 0xbfb8aa3b, v93
	v_exp_f32_e32 v97, v97
; DEV unsigned cvtpk(float lo, float hi) { f32x2_t v = {lo, hi}; bf16x2_t b = __builtin_convertvector(v, bf16x2_t); return __builtin_bit_cast(unsigned, b); }
; template <int MODE>
; DEV void gemm_phase(const bf16_t* __restrict__ A, const bf16_t* __restrict__ Bt, int M, int N, int K, bf16_t* __restrict__ Out, int ldo,
;                     const float* __restrict__ rstd, const float* __restrict__ rope) {
;     ...
;     if constexpr (MODE == G_GATEUP) {
; #pragma unroll
;       for (int ai = 0; ai < 2; ++ai)
; #pragma unroll
;         for (int m = 0; m < 4; ++m) {
;           const int row = brow + ai * HALF + wr * 64 + m * 16 + fr; const float rs = rstd[row];
;           float a8[8];
; #pragma unroll
;           for (int n = 0; n < 2; ++n)
; #pragma unroll
;             for (int j = 0; j < 4; ++j) { const float gv = acc[ai][0][m][n][j] * rs, uv = acc[ai][1][m][n][j] * rs;
;               a8[n * 4 + j] = gv * __builtin_amdgcn_rcpf(1.f + __builtin_amdgcn_exp2f(-gv * LOG2E)) * uv; }
;           u32x4 w = {cvtpk(a8[0], a8[1]), cvtpk(a8[2], a8[3]), cvtpk(a8[4], a8[5]), cvtpk(a8[6], a8[7])};
;           *reinterpret_cast<u32x4*>(Out + (size_t)row * ldo + pn * 128 + wc * 32 + fq * 8) = w; }
	v_pk_mul_f32 v[80:81], v[80:81], v[156:157] op_sel_hi:[1,0]
	v_pk_mul_f32 v[82:83], v[82:83], v[156:157] op_sel_hi:[1,0]
	v_add_f32_e32 v97, 1.0, v97
	v_rcp_f32_e32 v101, v97
	s_nop 0
	v_pk_mul_f32 v[92:93], v[92:93], v[100:101]
	s_nop 0
	v_pk_mul_f32 v[84:85], v[84:85], v[92:93]
	v_pk_mul_f32 v[92:93], v[94:95], v[156:157] op_sel_hi:[1,0]
	s_nop 0
	v_mul_f32_e32 v94, 0xbfb8aa3b, v92
	v_mul_f32_e32 v95, 0xbfb8aa3b, v93
	v_exp_f32_e32 v94, v94
	v_exp_f32_e32 v95, v95
	v_add_f32_e32 v94, 1.0, v94
	v_add_f32_e32 v95, 1.0, v95
	v_rcp_f32_e32 v94, v94
	v_rcp_f32_e32 v95, v95
	s_nop 0
	v_pk_mul_f32 v[92:93], v[92:93], v[94:95]
	s_nop 0
	v_pk_mul_f32 v[86:87], v[86:87], v[92:93]
	v_mul_f32_e32 v92, 0xbfb8aa3b, v88
	v_mul_f32_e32 v93, 0xbfb8aa3b, v89
	v_exp_f32_e32 v92, v92
	v_exp_f32_e32 v93, v93
	v_add_f32_e32 v92, 1.0, v92
	v_add_f32_e32 v93, 1.0, v93
	v_rcp_f32_e32 v92, v92
	v_rcp_f32_e32 v93, v93
	s_nop 0
	v_pk_mul_f32 v[88:89], v[88:89], v[92:93]
	s_nop 0
	v_pk_mul_f32 v[88:89], v[80:81], v[88:89]
	v_pk_mul_f32 v[80:81], v[90:91], v[156:157] op_sel_hi:[1,0]
	s_nop 0
	v_mul_f32_e32 v90, 0xbfb8aa3b, v80
	v_mul_f32_e32 v91, 0xbfb8aa3b, v81
	v_exp_f32_e32 v90, v90
	v_exp_f32_e32 v91, v91
	v_add_f32_e32 v90, 1.0, v90
	v_add_f32_e32 v91, 1.0, v91
	v_rcp_f32_e32 v90, v90
	v_rcp_f32_e32 v91, v91
	s_nop 0
	v_pk_mul_f32 v[80:81], v[80:81], v[90:91]
	s_nop 0
	v_pk_mul_f32 v[90:91], v[82:83], v[80:81]
	v_cvt_pk_bf16_f32 v80, v84, v85
	v_cvt_pk_bf16_f32 v81, v86, v87
	v_cvt_pk_bf16_f32 v82, v88, v89
	v_cvt_pk_bf16_f32 v83, v90, v91
	v_mad_i64_i32 v[84:85], s[18:19], v96, s9, v[140:141]
	global_store_dwordx4 v[84:85], v[80:83], off
	s_nop 1
	v_or_b32_e32 v80, 48, v142
	v_pk_mul_f32 v[76:77], v[76:77], v[158:159] op_sel_hi:[1,0]
	s_nop 0
	v_mul_f32_e32 v81, 0xbfb8aa3b, v76
	v_exp_f32_e32 v81, v81
	v_pk_mul_f32 v[68:69], v[68:69], v[158:159] op_sel_hi:[1,0]
	v_pk_mul_f32 v[70:71], v[70:71], v[158:159] op_sel_hi:[1,0]
	v_pk_mul_f32 v[72:73], v[72:73], v[158:159] op_sel_hi:[1,0]
	v_add_f32_e32 v81, 1.0, v81
	v_rcp_f32_e32 v84, v81
	v_mul_f32_e32 v81, 0xbfb8aa3b, v77
	v_exp_f32_e32 v81, v81
	v_pk_mul_f32 v[64:65], v[64:65], v[158:159] op_sel_hi:[1,0]
	v_pk_mul_f32 v[66:67], v[66:67], v[158:159] op_sel_hi:[1,0]
	v_add_f32_e32 v81, 1.0, v81
	v_rcp_f32_e32 v85, v81
	s_nop 0
	v_pk_mul_f32 v[76:77], v[76:77], v[84:85]
	s_nop 0
	v_pk_mul_f32 v[68:69], v[68:69], v[76:77]
	v_pk_mul_f32 v[76:77], v[78:79], v[158:159] op_sel_hi:[1,0]
	s_nop 0
	v_mul_f32_e32 v78, 0xbfb8aa3b, v76
	v_mul_f32_e32 v79, 0xbfb8aa3b, v77
	v_exp_f32_e32 v78, v78
	v_exp_f32_e32 v79, v79
	v_add_f32_e32 v78, 1.0, v78
	v_add_f32_e32 v79, 1.0, v79
	v_rcp_f32_e32 v78, v78
	v_rcp_f32_e32 v79, v79
	s_nop 0
	v_pk_mul_f32 v[76:77], v[76:77], v[78:79]
	s_nop 0
	v_pk_mul_f32 v[70:71], v[70:71], v[76:77]
	v_mul_f32_e32 v76, 0xbfb8aa3b, v72
	v_mul_f32_e32 v77, 0xbfb8aa3b, v73
	v_exp_f32_e32 v76, v76
	v_exp_f32_e32 v77, v77
	v_add_f32_e32 v76, 1.0, v76
	v_add_f32_e32 v77, 1.0, v77
	v_rcp_f32_e32 v76, v76
	v_rcp_f32_e32 v77, v77
	s_nop 0
	v_pk_mul_f32 v[72:73], v[72:73], v[76:77]
	s_nop 0
	v_pk_mul_f32 v[72:73], v[64:65], v[72:73]
	v_pk_mul_f32 v[64:65], v[74:75], v[158:159] op_sel_hi:[1,0]
	s_nop 0
	v_mul_f32_e32 v74, 0xbfb8aa3b, v64
	v_mul_f32_e32 v75, 0xbfb8aa3b, v65
	v_exp_f32_e32 v74, v74
	v_exp_f32_e32 v75, v75
	v_add_f32_e32 v74, 1.0, v74
	v_add_f32_e32 v75, 1.0, v75
	v_rcp_f32_e32 v74, v74
	v_rcp_f32_e32 v75, v75
	s_nop 0
	v_pk_mul_f32 v[64:65], v[64:65], v[74:75]
	s_nop 0
	v_pk_mul_f32 v[74:75], v[66:67], v[64:65]
	v_cvt_pk_bf16_f32 v64, v68, v69
	v_cvt_pk_bf16_f32 v65, v70, v71
	v_cvt_pk_bf16_f32 v66, v72, v73
	v_cvt_pk_bf16_f32 v67, v74, v75
	v_mad_i64_i32 v[68:69], s[18:19], v80, s9, v[140:141]
	global_store_dwordx4 v[68:69], v[64:67], off
	s_nop 1
	v_add_u32_e32 v64, 0x80, v142
	v_pk_mul_f32 v[60:61], v[60:61], v[160:161] op_sel_hi:[1,0]
	s_nop 0
	v_mul_f32_e32 v65, 0xbfb8aa3b, v60
	v_exp_f32_e32 v65, v65
	v_pk_mul_f32 v[52:53], v[52:53], v[160:161] op_sel_hi:[1,0]
	v_pk_mul_f32 v[54:55], v[54:55], v[160:161] op_sel_hi:[1,0]
	v_pk_mul_f32 v[56:57], v[56:57], v[160:161] op_sel_hi:[1,0]
	v_add_f32_e32 v65, 1.0, v65
	v_rcp_f32_e32 v68, v65
	v_mul_f32_e32 v65, 0xbfb8aa3b, v61
	v_exp_f32_e32 v65, v65
	v_pk_mul_f32 v[48:49], v[48:49], v[160:161] op_sel_hi:[1,0]
	v_pk_mul_f32 v[50:51], v[50:51], v[160:161] op_sel_hi:[1,0]
	v_add_f32_e32 v65, 1.0, v65
	v_rcp_f32_e32 v69, v65
	s_nop 0
	v_pk_mul_f32 v[60:61], v[60:61], v[68:69]
	s_nop 0
	v_pk_mul_f32 v[52:53], v[52:53], v[60:61]
	v_pk_mul_f32 v[60:61], v[62:63], v[160:161] op_sel_hi:[1,0]
	s_nop 0
	v_mul_f32_e32 v62, 0xbfb8aa3b, v60
	v_mul_f32_e32 v63, 0xbfb8aa3b, v61
	v_exp_f32_e32 v62, v62
	v_exp_f32_e32 v63, v63
	v_add_f32_e32 v62, 1.0, v62
	v_add_f32_e32 v63, 1.0, v63
	v_rcp_f32_e32 v62, v62
	v_rcp_f32_e32 v63, v63
	s_nop 0
	v_pk_mul_f32 v[60:61], v[60:61], v[62:63]
	s_nop 0
	v_pk_mul_f32 v[54:55], v[54:55], v[60:61]
	v_mul_f32_e32 v60, 0xbfb8aa3b, v56
	v_mul_f32_e32 v61, 0xbfb8aa3b, v57
	v_exp_f32_e32 v60, v60
	v_exp_f32_e32 v61, v61
	v_add_f32_e32 v60, 1.0, v60
	v_add_f32_e32 v61, 1.0, v61
	v_rcp_f32_e32 v60, v60
	v_rcp_f32_e32 v61, v61
	s_nop 0
	v_pk_mul_f32 v[56:57], v[56:57], v[60:61]
	s_nop 0
	v_pk_mul_f32 v[56:57], v[48:49], v[56:57]
	v_pk_mul_f32 v[48:49], v[58:59], v[160:161] op_sel_hi:[1,0]
	s_nop 0
	v_mul_f32_e32 v58, 0xbfb8aa3b, v48
	v_mul_f32_e32 v59, 0xbfb8aa3b, v49
	v_exp_f32_e32 v58, v58
	v_exp_f32_e32 v59, v59
	v_add_f32_e32 v58, 1.0, v58
	v_add_f32_e32 v59, 1.0, v59
	v_rcp_f32_e32 v58, v58
	v_rcp_f32_e32 v59, v59
	s_nop 0
	v_pk_mul_f32 v[48:49], v[48:49], v[58:59]
	s_nop 0
	v_pk_mul_f32 v[58:59], v[50:51], v[48:49]
; DEV unsigned cvtpk(float lo, float hi) { f32x2_t v = {lo, hi}; bf16x2_t b = __builtin_convertvector(v, bf16x2_t); return __builtin_bit_cast(unsigned, b); }
; #define BAR __builtin_amdgcn_s_barrier()
; template <int MODE>
; DEV void gemm_phase(const bf16_t* __restrict__ A, const bf16_t* __restrict__ Bt, int M, int N, int K, bf16_t* __restrict__ Out, int ldo,
;                     const float* __restrict__ rstd, const float* __restrict__ rope) {
;     ...
;     if constexpr (MODE == G_GATEUP) {
; #pragma unroll
;       for (int ai = 0; ai < 2; ++ai)
; #pragma unroll
;         for (int m = 0; m < 4; ++m) {
;           const int row = brow + ai * HALF + wr * 64 + m * 16 + fr; const float rs = rstd[row];
;           float a8[8];
; #pragma unroll
;           for (int n = 0; n < 2; ++n)
; #pragma unroll
;             for (int j = 0; j < 4; ++j) { const float gv = acc[ai][0][m][n][j] * rs, uv = acc[ai][1][m][n][j] * rs;
;               a8[n * 4 + j] = gv * __builtin_amdgcn_rcpf(1.f + __builtin_amdgcn_exp2f(-gv * LOG2E)) * uv; }
;           u32x4 w = {cvtpk(a8[0], a8[1]), cvtpk(a8[2], a8[3]), cvtpk(a8[4], a8[5]), cvtpk(a8[6], a8[7])};
;           *reinterpret_cast<u32x4*>(Out + (size_t)row * ldo + pn * 128 + wc * 32 + fq * 8) = w; }
;     ...
;     if (!has_next) break;
; #pragma unroll
;     for (int a = 0; a < 2; ++a)
; #pragma unroll
;       for (int b = 0; b < 2; ++b)
; #pragma unroll
;         for (int m = 0; m < 4; ++m)
; #pragma unroll
;           for (int n = 0; n < 2; ++n) acc[a][b][m][n] = (f32x4){0.f, 0.f, 0.f, 0.f};
;     pm = npm; pn = npn; cA = nA; cB = nB; L += (int)gridDim.x;
;     if (wr == 1) BAR;
	v_cvt_pk_bf16_f32 v48, v52, v53
	v_cvt_pk_bf16_f32 v49, v54, v55
	v_cvt_pk_bf16_f32 v50, v56, v57
	v_cvt_pk_bf16_f32 v51, v58, v59
	v_mad_i64_i32 v[52:53], s[18:19], v64, s9, v[140:141]
	global_store_dwordx4 v[52:53], v[48:51], off
	s_nop 1
	v_add_u32_e32 v48, 0x90, v142
	v_pk_mul_f32 v[44:45], v[44:45], v[162:163] op_sel_hi:[1,0]
	s_nop 0
	v_mul_f32_e32 v49, 0xbfb8aa3b, v44
	v_exp_f32_e32 v49, v49
	v_pk_mul_f32 v[36:37], v[36:37], v[162:163] op_sel_hi:[1,0]
	v_pk_mul_f32 v[38:39], v[38:39], v[162:163] op_sel_hi:[1,0]
	v_pk_mul_f32 v[40:41], v[40:41], v[162:163] op_sel_hi:[1,0]
	v_add_f32_e32 v49, 1.0, v49
	v_rcp_f32_e32 v52, v49
	v_mul_f32_e32 v49, 0xbfb8aa3b, v45
	v_exp_f32_e32 v49, v49
	v_pk_mul_f32 v[32:33], v[32:33], v[162:163] op_sel_hi:[1,0]
	v_pk_mul_f32 v[34:35], v[34:35], v[162:163] op_sel_hi:[1,0]
	v_add_f32_e32 v49, 1.0, v49
	v_rcp_f32_e32 v53, v49
	s_nop 0
	v_pk_mul_f32 v[44:45], v[44:45], v[52:53]
	s_nop 0
	v_pk_mul_f32 v[36:37], v[36:37], v[44:45]
	v_pk_mul_f32 v[44:45], v[46:47], v[162:163] op_sel_hi:[1,0]
	s_nop 0
	v_mul_f32_e32 v46, 0xbfb8aa3b, v44
	v_mul_f32_e32 v47, 0xbfb8aa3b, v45
	v_exp_f32_e32 v46, v46
	v_exp_f32_e32 v47, v47
	v_add_f32_e32 v46, 1.0, v46
	v_add_f32_e32 v47, 1.0, v47
	v_rcp_f32_e32 v46, v46
	v_rcp_f32_e32 v47, v47
	s_nop 0
	v_pk_mul_f32 v[44:45], v[44:45], v[46:47]
	s_nop 0
	v_pk_mul_f32 v[38:39], v[38:39], v[44:45]
	v_mul_f32_e32 v44, 0xbfb8aa3b, v40
	v_mul_f32_e32 v45, 0xbfb8aa3b, v41
	v_exp_f32_e32 v44, v44
	v_exp_f32_e32 v45, v45
	v_add_f32_e32 v44, 1.0, v44
	v_add_f32_e32 v45, 1.0, v45
	v_rcp_f32_e32 v44, v44
	v_rcp_f32_e32 v45, v45
	s_nop 0
	v_pk_mul_f32 v[40:41], v[40:41], v[44:45]
	s_nop 0
	v_pk_mul_f32 v[40:41], v[32:33], v[40:41]
	v_pk_mul_f32 v[32:33], v[42:43], v[162:163] op_sel_hi:[1,0]
	s_nop 0
	v_mul_f32_e32 v42, 0xbfb8aa3b, v32
	v_mul_f32_e32 v43, 0xbfb8aa3b, v33
	v_exp_f32_e32 v42, v42
	v_exp_f32_e32 v43, v43
	v_add_f32_e32 v42, 1.0, v42
	v_add_f32_e32 v43, 1.0, v43
	v_rcp_f32_e32 v42, v42
	v_rcp_f32_e32 v43, v43
	s_nop 0
	v_pk_mul_f32 v[32:33], v[32:33], v[42:43]
	s_nop 0
	v_pk_mul_f32 v[42:43], v[34:35], v[32:33]
	v_cvt_pk_bf16_f32 v32, v36, v37
	v_cvt_pk_bf16_f32 v33, v38, v39
	v_cvt_pk_bf16_f32 v34, v40, v41
	v_cvt_pk_bf16_f32 v35, v42, v43
	v_mad_i64_i32 v[36:37], s[18:19], v48, s9, v[140:141]
	global_store_dwordx4 v[36:37], v[32:35], off
	s_nop 1
	v_add_u32_e32 v32, 0xa0, v142
	v_pk_mul_f32 v[28:29], v[28:29], v[164:165] op_sel_hi:[1,0]
	s_nop 0
	v_mul_f32_e32 v33, 0xbfb8aa3b, v28
	v_exp_f32_e32 v33, v33
	v_pk_mul_f32 v[20:21], v[20:21], v[164:165] op_sel_hi:[1,0]
	v_pk_mul_f32 v[22:23], v[22:23], v[164:165] op_sel_hi:[1,0]
	v_pk_mul_f32 v[24:25], v[24:25], v[164:165] op_sel_hi:[1,0]
	v_add_f32_e32 v33, 1.0, v33
	v_rcp_f32_e32 v36, v33
	v_mul_f32_e32 v33, 0xbfb8aa3b, v29
	v_exp_f32_e32 v33, v33
	v_pk_mul_f32 v[16:17], v[16:17], v[164:165] op_sel_hi:[1,0]
	v_pk_mul_f32 v[18:19], v[18:19], v[164:165] op_sel_hi:[1,0]
	v_add_f32_e32 v33, 1.0, v33
	v_rcp_f32_e32 v37, v33
	s_nop 0
	v_pk_mul_f32 v[28:29], v[28:29], v[36:37]
	s_nop 0
	v_pk_mul_f32 v[20:21], v[20:21], v[28:29]
	v_pk_mul_f32 v[28:29], v[30:31], v[164:165] op_sel_hi:[1,0]
	s_nop 0
	v_mul_f32_e32 v30, 0xbfb8aa3b, v28
	v_mul_f32_e32 v31, 0xbfb8aa3b, v29
	v_exp_f32_e32 v30, v30
	v_exp_f32_e32 v31, v31
	v_add_f32_e32 v30, 1.0, v30
	v_add_f32_e32 v31, 1.0, v31
	v_rcp_f32_e32 v30, v30
	v_rcp_f32_e32 v31, v31
	s_nop 0
	v_pk_mul_f32 v[28:29], v[28:29], v[30:31]
	s_nop 0
	v_pk_mul_f32 v[22:23], v[22:23], v[28:29]
	v_mul_f32_e32 v28, 0xbfb8aa3b, v24
	v_mul_f32_e32 v29, 0xbfb8aa3b, v25
	v_exp_f32_e32 v28, v28
	v_exp_f32_e32 v29, v29
	v_add_f32_e32 v28, 1.0, v28
	v_add_f32_e32 v29, 1.0, v29
	v_rcp_f32_e32 v28, v28
	v_rcp_f32_e32 v29, v29
	s_nop 0
	v_pk_mul_f32 v[24:25], v[24:25], v[28:29]
	s_nop 0
	v_pk_mul_f32 v[24:25], v[16:17], v[24:25]
	v_pk_mul_f32 v[16:17], v[26:27], v[164:165] op_sel_hi:[1,0]
	s_nop 0
	v_mul_f32_e32 v26, 0xbfb8aa3b, v16
	v_mul_f32_e32 v27, 0xbfb8aa3b, v17
	v_exp_f32_e32 v26, v26
	v_exp_f32_e32 v27, v27
	v_add_f32_e32 v26, 1.0, v26
	v_add_f32_e32 v27, 1.0, v27
	v_rcp_f32_e32 v26, v26
	v_rcp_f32_e32 v27, v27
	s_nop 0
	v_pk_mul_f32 v[16:17], v[16:17], v[26:27]
	s_nop 0
	v_pk_mul_f32 v[26:27], v[18:19], v[16:17]
	v_cvt_pk_bf16_f32 v16, v20, v21
	v_cvt_pk_bf16_f32 v17, v22, v23
	v_cvt_pk_bf16_f32 v18, v24, v25
	v_cvt_pk_bf16_f32 v19, v26, v27
	v_mad_i64_i32 v[20:21], s[18:19], v32, s9, v[140:141]
	global_store_dwordx4 v[20:21], v[16:19], off
	s_nop 1
	v_add_u32_e32 v16, 0xb0, v142
	v_pk_mul_f32 v[12:13], v[12:13], v[166:167] op_sel_hi:[1,0]
	s_nop 0
	v_mul_f32_e32 v17, 0xbfb8aa3b, v12
	v_exp_f32_e32 v17, v17
	v_pk_mul_f32 v[8:9], v[8:9], v[166:167] op_sel_hi:[1,0]
	v_pk_mul_f32 v[10:11], v[10:11], v[166:167] op_sel_hi:[1,0]
	v_pk_mul_f32 v[4:5], v[4:5], v[166:167] op_sel_hi:[1,0]
	v_add_f32_e32 v17, 1.0, v17
	v_rcp_f32_e32 v20, v17
	v_mul_f32_e32 v17, 0xbfb8aa3b, v13
	v_exp_f32_e32 v17, v17
	v_pk_mul_f32 v[0:1], v[0:1], v[166:167] op_sel_hi:[1,0]
	v_pk_mul_f32 v[2:3], v[2:3], v[166:167] op_sel_hi:[1,0]
	v_add_f32_e32 v17, 1.0, v17
	v_rcp_f32_e32 v21, v17
	s_nop 0
	v_pk_mul_f32 v[12:13], v[12:13], v[20:21]
	s_nop 0
	v_pk_mul_f32 v[8:9], v[8:9], v[12:13]
	v_pk_mul_f32 v[12:13], v[14:15], v[166:167] op_sel_hi:[1,0]
	s_nop 0
	v_mul_f32_e32 v14, 0xbfb8aa3b, v12
	v_mul_f32_e32 v15, 0xbfb8aa3b, v13
	v_exp_f32_e32 v14, v14
	v_exp_f32_e32 v15, v15
	v_add_f32_e32 v14, 1.0, v14
	v_add_f32_e32 v15, 1.0, v15
	v_rcp_f32_e32 v14, v14
	v_rcp_f32_e32 v15, v15
	s_nop 0
	v_pk_mul_f32 v[12:13], v[12:13], v[14:15]
	s_nop 0
	v_pk_mul_f32 v[10:11], v[10:11], v[12:13]
	v_mul_f32_e32 v12, 0xbfb8aa3b, v4
	v_mul_f32_e32 v13, 0xbfb8aa3b, v5
	v_exp_f32_e32 v12, v12
	v_exp_f32_e32 v13, v13
	v_add_f32_e32 v12, 1.0, v12
	v_add_f32_e32 v13, 1.0, v13
	v_rcp_f32_e32 v12, v12
	v_rcp_f32_e32 v13, v13
	s_nop 0
	v_pk_mul_f32 v[4:5], v[4:5], v[12:13]
	s_nop 0
	v_pk_mul_f32 v[4:5], v[0:1], v[4:5]
	v_pk_mul_f32 v[0:1], v[6:7], v[166:167] op_sel_hi:[1,0]
	s_nop 0
	v_mul_f32_e32 v6, 0xbfb8aa3b, v0
	v_mul_f32_e32 v7, 0xbfb8aa3b, v1
	v_exp_f32_e32 v6, v6
	v_exp_f32_e32 v7, v7
	v_add_f32_e32 v6, 1.0, v6
	v_add_f32_e32 v7, 1.0, v7
	v_rcp_f32_e32 v6, v6
	v_rcp_f32_e32 v7, v7
	s_nop 0
	v_pk_mul_f32 v[0:1], v[0:1], v[6:7]
	s_nop 0
	v_pk_mul_f32 v[6:7], v[2:3], v[0:1]
	v_cvt_pk_bf16_f32 v2, v4, v5
	v_mad_i64_i32 v[4:5], s[18:19], v16, s9, v[140:141]
	v_cvt_pk_bf16_f32 v0, v8, v9
	v_cvt_pk_bf16_f32 v1, v10, v11
	v_cvt_pk_bf16_f32 v3, v6, v7
	s_mov_b64 s[18:19], -1
	global_store_dwordx4 v[4:5], v[0:3], off
	s_cbranch_vccnz .LBB0_614
	s_andn2_b64 vcc, exec, s[0:1]
	s_cbranch_vccnz .LBB0_613
	s_barrier
	s_branch .LBB0_613
